# P0: odd workgroups defer the GT computation to the end of P0 (HBM streaming and LDS-bound GT work overlap across workgroups) + XCD-local seams + P4/P6' epilogue rewrites
# baseline (speedup 1.0000x reference)
.LBB0_32:
	s_or_b64 exec, exec, s[0:1]
	s_mov_b32 s98, 0
	s_lshl_b32 s23, s2, 3
	s_lshl_b32 s22, s3, 3
	s_add_u32 s40, s66, 0x100000
	s_addc_u32 s41, s67, 0
	s_cmpk_gt_i32 s2, 0xff
	s_cbranch_scc1 .LBB0_43
	s_bitcmp1_b32 s2, 0
	s_cbranch_scc0 .Lgt_entry
	s_mov_b32 s98, 1
	s_branch .LBB0_43
.Lgt_entry:
	v_and_b32_e32 v0, 0x7f, v66
	v_cvt_f32_ubyte0_e32 v1, v0
	v_mul_f32_e32 v1, 0x3c000000, v1
	v_cos_f32_e32 v2, v1
	v_sin_f32_e64 v1, -v1
	s_movk_i32 s21, 0x80
	v_cmp_gt_u32_e32 vcc, s21, v66
	v_lshl_add_u32 v11, v0, 2, 0
	v_lshlrev_b32_e32 v0, 9, v0
	v_cndmask_b32_e32 v5, v1, v2, vcc
	v_lshrrev_b32_e32 v1, 6, v66
	v_and_b32_e32 v9, 14, v1
	v_mov_b32_e32 v1, 0
	v_lshrrev_b32_e32 v12, 7, v66
	s_movk_i32 s0, 0x100
	s_add_i32 s21, 0, 0x10000
	v_lshl_add_u64 v[2:3], s[40:41], 0, v[0:1]
	v_or_b32_e32 v0, 0x400, v66
	v_or_b32_e32 v14, 0x800, v66
	v_or_b32_e32 v16, 0xc00, v66
	v_lshlrev_b32_e32 v25, 4, v12
	v_cmp_gt_u32_e64 s[0:1], s0, v66
	s_movk_i32 s20, 0x7f
	v_lshl_add_u32 v7, v66, 2, s21
	v_lshl_add_u32 v24, v66, 4, 0
	v_or_b32_e32 v26, 8, v25
	v_mul_u32_u24_e32 v4, 14, v12
	v_mul_u32_u24_e32 v6, 12, v12
	v_mul_u32_u24_e32 v8, 10, v12
	v_lshlrev_b32_e32 v27, 3, v12
	v_mul_u32_u24_e32 v10, 6, v12
	v_lshlrev_b32_e32 v28, 2, v12
	v_lshlrev_b32_e32 v12, 4, v66
	v_mov_b32_e32 v13, v1
	v_lshlrev_b32_e32 v29, 4, v0
	v_lshlrev_b32_e32 v30, 4, v14
	v_lshlrev_b32_e32 v31, 4, v16
	s_mov_b32 s24, s23
	s_mov_b32 s25, s2
	s_branch .LBB0_35

.LBB0_43:
	s_cmp_eq_u32 s98, 2
	s_cbranch_scc1 .Lgt_back
	s_lshr_b32 s0, s26, 6
	s_add_i32 s24, s0, s23
	s_add_u32 s76, s66, 0x200000
	v_writelane_b32 v254, s40, 1
	s_addc_u32 s77, s67, 0
	s_add_u32 s42, s66, 0xe00000
	v_writelane_b32 v254, s41, 2
	s_addc_u32 s43, s67, 0
	v_writelane_b32 v254, s0, 3
	s_lshl_b32 s0, s0, 14
	s_add_i32 s25, s0, 0
	v_and_b32_e32 v38, 63, v66
	s_cmpk_gt_i32 s24, 0x9ff
	s_mov_b32 s1, 0
	s_cbranch_scc1 .LBB0_50
	v_lshrrev_b32_e32 v3, 3, v38
	v_and_b32_e32 v5, 6, v3
	v_lshlrev_b32_e32 v2, 11, v5
	v_mul_u32_u24_e32 v20, 0xc00, v5
	v_or_b32_e32 v5, 1, v3
	v_mul_u32_u24_e32 v22, 0xc00, v5
	v_or_b32_e32 v5, 9, v3
	v_mul_u32_u24_e32 v24, 0xc00, v5
	v_or_b32_e32 v5, 17, v3
	v_mul_u32_u24_e32 v26, 0xc00, v5
	v_or_b32_e32 v5, 25, v3
	v_mul_u32_u24_e32 v28, 0xc00, v5
	v_or_b32_e32 v5, 33, v3
	v_mul_u32_u24_e32 v30, 0xc00, v5
	v_or_b32_e32 v5, 41, v3
	v_readlane_b32 s0, v254, 3
	v_lshlrev_b32_e32 v0, 2, v66
	v_lshlrev_b32_e32 v7, 11, v3
	v_mul_u32_u24_e32 v32, 0xc00, v5
	v_or_b32_e32 v5, 49, v3
	v_or_b32_e32 v3, 57, v3
	s_lshl_b32 s0, s0, 6
	v_and_b32_e32 v0, 60, v0
	v_or_b32_e32 v4, 0x800, v7
	v_or_b32_e32 v6, 0x4800, v7
	v_or_b32_e32 v8, 0x8800, v7
	v_or_b32_e32 v10, 0xc800, v7
	v_or_b32_e32 v12, 0x10800, v7
	v_or_b32_e32 v14, 0x14800, v7
	v_or_b32_e32 v16, 0x18800, v7
	v_or_b32_e32 v18, 0x1c800, v7
	v_mul_u32_u24_e32 v34, 0xc00, v5
	v_mul_u32_u24_e32 v36, 0xc00, v3
	s_add_i32 s0, s78, s0
	v_mov_b32_e32 v1, 0
	s_add_i32 s20, s0, 0xfffe8000
	s_add_i32 s27, s24, 0xfffffa00
	v_lshlrev_b32_e32 v2, 2, v2
	v_lshlrev_b32_e32 v4, 2, v4
	s_mov_b32 s28, 0x10000
	v_lshlrev_b32_e32 v6, 2, v6
	s_mov_b32 s29, 0x20000
	v_lshlrev_b32_e32 v8, 2, v8
	s_mov_b32 s30, 0x30000
	v_lshlrev_b32_e32 v10, 2, v10
	s_mov_b32 s31, 0x40000
	v_lshlrev_b32_e32 v12, 2, v12
	s_mov_b32 s33, 0x50000
	v_lshlrev_b32_e32 v14, 2, v14
	s_mov_b32 s34, 0x60000
	v_lshlrev_b32_e32 v16, 2, v16
	s_mov_b32 s35, 0x70000
	v_lshlrev_b32_e32 v18, 2, v18
	s_movk_i32 s38, 0x70
	s_movk_i32 s39, 0x50
	s_movk_i32 s40, 0x60
	s_mov_b32 s41, 0x18000
	v_lshlrev_b32_e32 v20, 2, v20
	v_lshlrev_b32_e32 v22, 2, v22
	v_lshlrev_b32_e32 v24, 2, v24
	v_lshlrev_b32_e32 v26, 2, v26
	s_mov_b32 s45, 0x48000
	v_lshlrev_b32_e32 v28, 2, v28
	v_lshlrev_b32_e32 v30, 2, v30
	s_mov_b32 s46, 0x78000
	v_lshlrev_b32_e32 v32, 2, v32
	s_mov_b32 s47, 0x90000
	v_lshlrev_b32_e32 v34, 2, v34
	s_mov_b32 s48, 0xa8000
	v_lshlrev_b32_e32 v36, 2, v36
	v_lshlrev_b32_e32 v0, 2, v0
	s_mov_b32 s49, s24
	s_branch .LBB0_46

.LBB0_58:
	s_or_b64 exec, exec, s[0:1]
	s_cmp_lg_u32 s98, 1
	s_cbranch_scc1 .Lgt_return
	s_mov_b32 s98, 2
	s_mov_b32 s99, s24
	s_mov_b32 s100, s25
	v_readlane_b32 s40, v254, 1
	v_readlane_b32 s41, v254, 2
	v_readlane_b32 s10, v255, 1
	v_readlane_b32 s11, v255, 2
	s_nop 3
	s_load_dwordx2 s[10:11], s[10:11], 0x18
	s_waitcnt lgkmcnt(0)
	s_barrier
	s_branch .Lgt_entry
.Lgt_back:
	v_mbcnt_lo_u32_b32 v65, -1, 0
	s_mov_b32 s24, s99
	s_mov_b32 s25, s100
	s_mov_b32 s98, 3
.Lgt_return:
	v_mbcnt_lo_u32_b32 v0, -1, 0
	v_mbcnt_hi_u32_b32 v0, -1, v0
	s_waitcnt vmcnt(0)
	s_and_b32 s0, s26, 0xffffffc0
	v_sub_u32_e32 v0, 0, v0
	v_cmp_eq_u32_e32 vcc, s0, v0
	s_barrier
	v_writelane_b32 v254, s0, 6
	s_and_saveexec_b64 s[0:1], vcc
	v_writelane_b32 v254, s64, 7
	s_nop 1
	v_writelane_b32 v254, s65, 8
	v_writelane_b32 v254, s66, 9
	v_writelane_b32 v254, s67, 10
	v_writelane_b32 v254, s42, 11
	v_writelane_b32 v254, s43, 12
	s_cbranch_execz .LBB0_110
	s_add_i32 s4, 0, 0x20400
	v_mov_b32_e32 v0, s4
	s_waitcnt vmcnt(0) expcnt(0) lgkmcnt(0)
	ds_read_b32 v2, v0
	s_add_i32 s4, 0, 0x20404
	v_mov_b32_e32 v0, s4
	ds_read_b32 v0, v0
	s_waitcnt lgkmcnt(1)
	v_cmp_ne_u32_e32 vcc, 0, v2
	s_cbranch_vccnz .LBB0_74
	s_add_u32 s4, s66, 0x40200
	s_addc_u32 s5, s67, 0
	s_add_u32 s6, s66, 0x40400
	s_addc_u32 s7, s67, 0
	s_add_u32 s10, s66, 0x40500
	s_addc_u32 s11, s67, 0
	s_add_u32 s18, s66, 0x40600
	s_addc_u32 s19, s67, 0
	s_add_u32 s34, s66, 0x40700
	s_addc_u32 s35, s67, 0
	s_add_u32 s46, s66, 0x40800
	s_addc_u32 s47, s67, 0
	s_add_u32 s48, s66, 0x40900
	s_addc_u32 s49, s67, 0
	s_add_u32 s50, s66, 0x40a00
	s_addc_u32 s51, s67, 0
	s_add_u32 s52, s66, 0x40b00
	s_addc_u32 s53, s67, 0
	s_add_u32 s54, s66, 0x40c00
	s_addc_u32 s55, s67, 0
	s_add_u32 s56, s66, 0x40d00
	s_addc_u32 s57, s67, 0
	s_add_u32 s58, s66, 0x40e00
	s_addc_u32 s59, s67, 0
	s_add_u32 s60, s66, 0x40f00
	s_addc_u32 s61, s67, 0
	s_add_u32 s62, s66, 0x41000
	s_mov_b64 s[28:29], s[64:65]
	s_addc_u32 s63, s67, 0
	s_mov_b64 s[30:31], s[66:67]
	s_add_u32 s64, s30, 0x41100
	s_addc_u32 s65, s31, 0
	s_add_u32 s66, s30, 0x41200
	s_addc_u32 s67, s31, 0
	s_add_u32 s68, s30, 0x41300
	s_addc_u32 s69, s31, 0
	s_mov_b32 s20, 1
	v_mov_b32_e32 v16, 0
	s_branch .LBB0_62
